# final row pass: output stores write-through (sc0 sc1) + nt, so no dirty output lines remain in L2 at kernel end
# baseline (speedup 1.0000x reference)
.Lrp4_skip:
	v_lshlrev_b32_e32 v66, 16, v42
	v_and_b32_e32 v67, 0xffff0000, v42
	v_alignbit_b32 v42, v43, v42, 16
	v_and_b32_e32 v43, 0xffff0000, v43
	v_lshlrev_b32_e32 v68, 16, v44
	v_and_b32_e32 v69, 0xffff0000, v44
	v_alignbit_b32 v44, v45, v44, 16
	v_and_b32_e32 v45, 0xffff0000, v45
	v_lshlrev_b32_e32 v70, 16, v46
	v_and_b32_e32 v71, 0xffff0000, v46
	v_alignbit_b32 v46, v47, v46, 16
	v_and_b32_e32 v47, 0xffff0000, v47
	v_and_b32_e32 v42, 0xffff0000, v42
	v_and_b32_e32 v44, 0xffff0000, v44
	v_mul_f32_e32 v74, v67, v67
	v_mul_f32_e32 v75, v43, v43
	v_mul_f32_e32 v76, v69, v69
	v_mul_f32_e32 v77, v45, v45
	v_lshlrev_b32_e32 v72, 16, v48
	v_and_b32_e32 v73, 0xffff0000, v48
	v_alignbit_b32 v48, v49, v48, 16
	v_and_b32_e32 v49, 0xffff0000, v49
	v_and_b32_e32 v46, 0xffff0000, v46
	v_mul_f32_e32 v78, v71, v71
	v_mul_f32_e32 v79, v47, v47
	v_fmac_f32_e32 v74, v66, v66
	v_fmac_f32_e32 v75, v42, v42
	v_fmac_f32_e32 v76, v68, v68
	v_fmac_f32_e32 v77, v44, v44
	v_and_b32_e32 v48, 0xffff0000, v48
	v_mul_f32_e32 v80, v73, v73
	v_mul_f32_e32 v81, v49, v49
	v_fmac_f32_e32 v78, v70, v70
	v_fmac_f32_e32 v79, v46, v46
	v_add_f32_e32 v74, v74, v75
	v_add_f32_e32 v75, v76, v77
	v_fmac_f32_e32 v80, v72, v72
	v_fmac_f32_e32 v81, v48, v48
	v_add_f32_e32 v76, v78, v79
	v_add_f32_e32 v74, v74, v75
	v_add_f32_e32 v77, v80, v81
	v_add_f32_e32 v74, v74, v76
	v_add_f32_e32 v76, v74, v77
	ds_bpermute_b32 v77, v58, v76
	v_and_b32_e32 v81, 0xffff0000, v55
	v_and_b32_e32 v83, 0xffff0000, v56
	v_and_b32_e32 v85, 0xffff0000, v57
	v_lshlrev_b32_e32 v74, 16, v50
	s_waitcnt lgkmcnt(0)
	v_add_f32_e32 v78, v76, v77
	ds_bpermute_b32 v79, v59, v78
	v_and_b32_e32 v75, 0xffff0000, v50
	v_alignbit_b32 v50, v51, v50, 16
	v_lshlrev_b32_e32 v76, 16, v52
	v_and_b32_e32 v77, 0xffff0000, v52
	s_waitcnt lgkmcnt(0)
	v_add_f32_e32 v80, v78, v79
	ds_bpermute_b32 v82, v60, v80
	v_lshlrev_b32_e32 v78, 16, v54
	v_and_b32_e32 v79, 0xffff0000, v54
	v_alignbit_b32 v54, v55, v54, 16
	v_alignbit_b32 v52, v53, v52, 16
	s_waitcnt lgkmcnt(0)
	v_add_f32_e32 v55, v80, v82
	ds_bpermute_b32 v80, v61, v55
	v_lshlrev_b32_e32 v82, 16, v56
	v_alignbit_b32 v56, v57, v56, 16
	v_and_b32_e32 v84, 0xffff0000, v56
	v_pk_mul_f32 v[42:43], v[2:3], v[42:43]
	s_waitcnt lgkmcnt(0)
	v_add_f32_e32 v55, v55, v80
	ds_bpermute_b32 v57, v62, v55
	v_and_b32_e32 v80, 0xffff0000, v54
	v_pk_mul_f32 v[44:45], v[14:15], v[44:45]
	v_and_b32_e32 v51, 0xffff0000, v51
	v_and_b32_e32 v53, 0xffff0000, v53
	s_waitcnt lgkmcnt(0)
	v_add_f32_e32 v86, v55, v57
	ds_bpermute_b32 v87, v63, v86
	v_pk_mul_f32 v[54:55], v[0:1], v[66:67]
	v_pk_mul_f32 v[66:67], v[16:17], v[70:71]
	v_pk_mul_f32 v[56:57], v[12:13], v[68:69]
	v_pk_mul_f32 v[68:69], v[28:29], v[72:73]
	s_waitcnt lgkmcnt(0)
	v_add_f32_e32 v70, v86, v87
	v_fmamk_f32 v70, v70, 0x3a800000, v64
	v_mul_f32_e32 v71, 0x4f800000, v70
	v_cmp_gt_f32_e32 vcc, s17, v70
	v_and_b32_e32 v50, 0xffff0000, v50
	v_and_b32_e32 v52, 0xffff0000, v52
	v_cndmask_b32_e32 v70, v70, v71, vcc
	v_sqrt_f32_e32 v71, v70
	v_pk_mul_f32 v[46:47], v[18:19], v[46:47]
	v_pk_mul_f32 v[48:49], v[30:31], v[48:49]
	v_add_u32_e32 v72, -1, v71
	v_add_u32_e32 v73, 1, v71
	v_fma_f32 v86, -v72, v71, v70
	v_fma_f32 v87, -v73, v71, v70
	v_cmp_ge_f32_e64 s[2:3], 0, v86
	s_nop 1
	v_cndmask_b32_e64 v71, v71, v72, s[2:3]
	v_cmp_lt_f32_e64 s[2:3], 0, v87
	s_nop 1
	v_cndmask_b32_e64 v71, v71, v73, s[2:3]
	v_mul_f32_e32 v72, 0x37800000, v71
	v_cndmask_b32_e32 v71, v71, v72, vcc
	v_cmp_class_f32_e32 vcc, v70, v65
	s_nop 1
	v_cndmask_b32_e32 v70, v71, v70, vcc
	v_div_scale_f32 v71, s[2:3], v70, v70, 0.5
	v_rcp_f32_e32 v72, v71
	v_div_scale_f32 v73, vcc, 0.5, v70, 0.5
	v_fma_f32 v86, -v71, v72, 1.0
	v_fmac_f32_e32 v72, v86, v72
	v_mul_f32_e32 v86, v73, v72
	v_fma_f32 v87, -v71, v86, v73
	v_fmac_f32_e32 v86, v87, v72
	v_fma_f32 v71, -v71, v86, v73
	v_div_fmas_f32 v71, v71, v72, v86
	v_div_fixup_f32 v70, v71, v70, 0.5
	v_pk_mul_f32 v[72:73], v[54:55], v[70:71] op_sel_hi:[1,0]
	v_pk_mul_f32 v[42:43], v[42:43], v[70:71] op_sel_hi:[1,0]
	v_pk_mul_f32 v[86:87], v[56:57], v[70:71] op_sel_hi:[1,0]
	v_pk_mul_f32 v[44:45], v[44:45], v[70:71] op_sel_hi:[1,0]
	v_pk_mul_f32 v[66:67], v[66:67], v[70:71] op_sel_hi:[1,0]
	v_pk_mul_f32 v[46:47], v[46:47], v[70:71] op_sel_hi:[1,0]
	v_pk_fma_f32 v[54:55], v[32:33], v[50:51], v[42:43] op_sel_hi:[0,1,1]
	v_pk_fma_f32 v[56:57], v[32:33], v[74:75], v[72:73] op_sel_hi:[0,1,1]
	v_pk_fma_f32 v[50:51], v[32:33], v[52:53], v[44:45] op_sel_hi:[0,1,1]
	v_pk_fma_f32 v[52:53], v[32:33], v[76:77], v[86:87] op_sel_hi:[0,1,1]
	v_pk_fma_f32 v[42:43], v[32:33], v[80:81], v[46:47] op_sel_hi:[0,1,1]
	v_pk_fma_f32 v[46:47], v[32:33], v[78:79], v[66:67] op_sel_hi:[0,1,1]
	v_mul_f32_e32 v44, v57, v57
	v_mul_f32_e32 v45, v55, v55
	v_mul_f32_e32 v66, v53, v53
	v_mul_f32_e32 v67, v51, v51
	v_pk_mul_f32 v[68:69], v[68:69], v[70:71] op_sel_hi:[1,0]
	v_mul_f32_e32 v71, v47, v47
	v_mul_f32_e32 v72, v43, v43
	v_fmac_f32_e32 v44, v56, v56
	v_fmac_f32_e32 v45, v54, v54
	v_fmac_f32_e32 v66, v52, v52
	v_fmac_f32_e32 v67, v50, v50
	v_fmac_f32_e32 v71, v46, v46
	v_fmac_f32_e32 v72, v42, v42
	v_add_f32_e32 v44, v44, v45
	v_add_f32_e32 v45, v66, v67
	v_add_f32_e32 v66, v71, v72
	v_add_f32_e32 v44, v44, v45
	v_add_f32_e32 v66, v66, v44
	v_pk_mul_f32 v[44:45], v[48:49], v[70:71] op_sel_hi:[1,0]
	v_pk_fma_f32 v[48:49], v[32:33], v[82:83], v[68:69] op_sel_hi:[0,1,1]
	v_pk_fma_f32 v[44:45], v[32:33], v[84:85], v[44:45] op_sel_hi:[0,1,1]
	v_mul_f32_e32 v32, v49, v49
	v_mul_f32_e32 v67, v45, v45
	v_fmac_f32_e32 v32, v48, v48
	v_fmac_f32_e32 v67, v44, v44
	v_add_f32_e32 v32, v32, v67
	v_add_f32_e32 v32, v32, v66
	ds_bpermute_b32 v66, v58, v32
	s_waitcnt lgkmcnt(0)
	v_add_f32_e32 v32, v32, v66
	ds_bpermute_b32 v66, v59, v32
	s_waitcnt lgkmcnt(0)
	v_add_f32_e32 v32, v32, v66
	ds_bpermute_b32 v66, v60, v32
	s_waitcnt lgkmcnt(0)
	v_add_f32_e32 v32, v32, v66
	ds_bpermute_b32 v66, v61, v32
	s_waitcnt lgkmcnt(0)
	v_add_f32_e32 v32, v32, v66
	ds_bpermute_b32 v66, v62, v32
	s_waitcnt lgkmcnt(0)
	v_add_f32_e32 v32, v32, v66
	ds_bpermute_b32 v66, v63, v32
	s_waitcnt lgkmcnt(0)
	v_add_f32_e32 v32, v32, v66
	v_fmamk_f32 v32, v32, 0x3a800000, v64
	v_mul_f32_e32 v66, 0x4f800000, v32
	v_cmp_gt_f32_e32 vcc, s17, v32
	s_nop 1
	v_cndmask_b32_e32 v32, v32, v66, vcc
	v_sqrt_f32_e32 v66, v32
	s_nop 0
	v_add_u32_e32 v67, -1, v66
	v_add_u32_e32 v68, 1, v66
	v_fma_f32 v69, -v67, v66, v32
	v_fma_f32 v70, -v68, v66, v32
	v_cmp_ge_f32_e64 s[2:3], 0, v69
	s_nop 1
	v_cndmask_b32_e64 v66, v66, v67, s[2:3]
	v_cmp_lt_f32_e64 s[2:3], 0, v70
	s_nop 1
	v_cndmask_b32_e64 v66, v66, v68, s[2:3]
	v_mul_f32_e32 v67, 0x37800000, v66
	v_cndmask_b32_e32 v66, v66, v67, vcc
	v_cmp_class_f32_e32 vcc, v32, v65
	s_nop 1
	v_cndmask_b32_e32 v66, v66, v32, vcc
	v_div_scale_f32 v32, s[2:3], v66, v66, 1.0
	v_rcp_f32_e32 v67, v32
	v_div_scale_f32 v68, vcc, 1.0, v66, 1.0
	s_and_b64 s[2:3], exec, s[4:5]
	v_fma_f32 v69, -v32, v67, 1.0
	v_fmac_f32_e32 v67, v69, v67
	v_mul_f32_e32 v69, v68, v67
	v_fma_f32 v70, -v32, v69, v68
	v_fmac_f32_e32 v69, v70, v67
	v_fma_f32 v32, -v32, v69, v68
	v_div_fmas_f32 v32, v32, v67, v69
	v_div_fixup_f32 v32, v32, v66, 1.0
	s_mov_b64 vcc, s[2:3]
	s_cbranch_vccz .LBB0_1484
	s_lshl_b64 s[2:3], s[10:11], 10
	v_pk_mul_f32 v[70:71], v[10:11], v[54:55]
	v_pk_mul_f32 v[68:69], v[8:9], v[56:57]
	v_lshl_add_u64 v[72:73], s[2:3], 2, v[38:39]
	v_pk_mul_f32 v[68:69], v[68:69], v[32:33] op_sel_hi:[1,0]
	v_pk_mul_f32 v[70:71], v[70:71], v[32:33] op_sel_hi:[1,0]
	global_store_dwordx4 v[72:73], v[68:71], off sc0 sc1 nt
	s_nop 1
	v_pk_mul_f32 v[70:71], v[6:7], v[50:51]
	v_pk_mul_f32 v[68:69], v[4:5], v[52:53]
	v_pk_mul_f32 v[70:71], v[70:71], v[32:33] op_sel_hi:[1,0]
	v_pk_mul_f32 v[68:69], v[68:69], v[32:33] op_sel_hi:[1,0]
	global_store_dwordx4 v[72:73], v[68:71], off offset:1024 sc0 sc1 nt
	s_nop 1
	v_pk_mul_f32 v[70:71], v[26:27], v[42:43]
	v_pk_mul_f32 v[68:69], v[24:25], v[46:47]
	v_pk_mul_f32 v[70:71], v[70:71], v[32:33] op_sel_hi:[1,0]
	v_pk_mul_f32 v[68:69], v[68:69], v[32:33] op_sel_hi:[1,0]
	global_store_dwordx4 v[72:73], v[68:71], off offset:2048 sc0 sc1 nt
	s_nop 1
	v_pk_mul_f32 v[70:71], v[22:23], v[44:45]
	v_pk_mul_f32 v[68:69], v[20:21], v[48:49]
	v_pk_mul_f32 v[70:71], v[70:71], v[32:33] op_sel_hi:[1,0]
	v_pk_mul_f32 v[68:69], v[68:69], v[32:33] op_sel_hi:[1,0]
	global_store_dwordx4 v[72:73], v[68:71], off offset:3072 sc0 sc1 nt
	s_cbranch_execnz .LBB0_1481
	s_branch .LBB0_1485
